# v23 + attention: q-gains loaded once per unit, next-subtile Q rows requested after the rope block and waited for only at the end of the iteration
# speedup vs baseline: 1.0025x; 1.0025x over previous
; __device__ __forceinline__ void norm_rope(u32x4 w0, u32x4 w1, const float* __restrict__ gain, int chunk, const float* rp, float scale, float* x) {
;     const unsigned ww[8] = {w0.x, w0.y, w0.z, w0.w, w1.x, w1.y, w1.z, w1.w};
;     float ss = 0.f;
; #pragma unroll
;     for (int i = 0; i < 8; ++i) { x[2 * i] = __uint_as_float(ww[i] << 16); x[2 * i + 1] = __uint_as_float(ww[i] & 0xffff0000u); ss += x[2 * i] * x[2 * i] + x[2 * i + 1] * x[2 * i + 1]; }
;     ss += dpp_perm<0xB1, 0xF>(ss); ss += dpp_perm<0x4E, 0xF>(ss);
;     const float inv = rsqrtf(ss * (1.0f / 64.0f) + 1e-6f);
; #pragma unroll
;     for (int i = 0; i < 16; ++i) x[i] = x[i] * inv * gain[chunk * 16 + i];
;     if (chunk == 0) rope16(x, rp);
; #pragma unroll
;     for (int i = 0; i < 16; ++i) x[i] *= scale;
; __device__ __forceinline__ void attn_unit(const AtArgs& A, unsigned char* lds, int unit, int tid, int wave, int lane) {
;     ...
;             { const bf16* pn = pq0 + (size_t)((st < 3) ? st + 1 : 3) * 16 * QW; qn0 = *(const u32x4*)pn; qn1 = *(const u32x4*)(pn + 8); }
;             norm_rope(qc0, qc1, A.qg, chunk, ROPE + t * 16, 0.125f, x);
;             u32x4 o0, o1; o0.x = pk2(x[0], x[1]); o0.y = pk2(x[2], x[3]); o0.z = pk2(x[4], x[5]); o0.w = pk2(x[6], x[7]); o1.x = pk2(x[8], x[9]); o1.y = pk2(x[10], x[11]); o1.z = pk2(x[12], x[13]); o1.w = pk2(x[14], x[15]);
;             *(u32x4*)(QS + row * QST + chunk * 16) = o0; *(u32x4*)(QS + row * QST + chunk * 16 + 8) = o1;
;         }
;         LDS_WAIT();
;         const bf16x8 qa0 = *(const bf16x8*)(QS + fr * QST + fq * 8), qa1 = *(const bf16x8*)(QS + fr * QST + 32 + fq * 8);
;         f32x4 sc[9];
; #pragma unroll
;         for (int kt = 0; kt < 9; ++kt) {
;             const int key = (q0 / 16 + kt) * 16 + fr;
;             const bf16x8 kb0 = *(const bf16x8*)(KS + key * KST + fq * 8), kb1 = *(const bf16x8*)(KS + key * KST + 32 + fq * 8);
;             f32x4 a = (f32x4){0.f, 0.f, 0.f, 0.f};
;             a = __builtin_amdgcn_mfma_f32_16x16x32_bf16(qa0, kb0, a, 0, 0, 0); a = __builtin_amdgcn_mfma_f32_16x16x32_bf16(qa1, kb1, a, 0, 0, 0);
; #pragma unroll
;             for (int r = 0; r < 4; ++r) {
;                 const int qi = q0 + fq * 4 + r;
;                 const bool ok = (key > qi) && (key <= qi + 128) && (nb > 0 || key >= 128);
;                 a[r] = ok ? a[r] : -1e30f;
;             }
;             sc[kt] = a;
;         }
.Lattn_noprio:
	global_load_dwordx4 v[140:143], v[44:45], off offset:48
	global_load_dwordx4 v[136:139], v[44:45], off offset:32
	global_load_dwordx4 v[132:135], v[44:45], off offset:16
	global_load_dwordx4 v[128:131], v[44:45], off
	s_waitcnt vmcnt(0)
	s_branch .LBB0_511
.LBB0_510:
	s_or_b64 exec, exec, s[0:1]
	s_cmp_lg_u32 s2, 48
	s_cselect_b32 s6, s3, 0x21000
	v_lshl_add_u64 v[4:5], s[6:7], 1, v[50:51]
	global_load_dwordx4 v[0:3], v[4:5], off offset:16
	s_nop 0
	global_load_dwordx4 v[4:7], v[4:5], off
	s_nop 0
	v_pk_mul_f32 v[18:19], v[60:61], s[14:15] op_sel_hi:[1,0]
	v_pk_mul_f32 v[20:21], v[28:29], s[14:15] op_sel_hi:[1,0]
	v_pk_mul_f32 v[22:23], v[24:25], s[14:15] op_sel_hi:[1,0]
	v_pk_mul_f32 v[12:13], v[12:13], s[14:15] op_sel_hi:[1,0]
	v_pk_mul_f32 v[24:25], v[8:9], s[14:15] op_sel_hi:[1,0]
	v_pk_mul_f32 v[26:27], v[10:11], s[14:15] op_sel_hi:[1,0]
	v_pk_mul_f32 v[14:15], v[14:15], s[14:15] op_sel_hi:[1,0]
	v_pk_mul_f32 v[16:17], v[16:17], s[14:15] op_sel_hi:[1,0]
	v_cvt_pk_bf16_f32 v8, v18, v19
	v_cvt_pk_bf16_f32 v9, v20, v21
	v_cvt_pk_bf16_f32 v10, v22, v23
	v_cvt_pk_bf16_f32 v11, v12, v13
	v_cvt_pk_bf16_f32 v12, v24, v25
	v_cvt_pk_bf16_f32 v13, v26, v27
	v_cvt_pk_bf16_f32 v14, v14, v15
	v_cvt_pk_bf16_f32 v15, v16, v17
	ds_write_b128 v75, v[8:11]
	ds_write_b128 v75, v[12:15] offset:16
	s_waitcnt lgkmcnt(0)
	ds_read_b128 v[12:15], v76
	ds_read_b128 v[8:11], v76 offset:64
	ds_read_b128 v[16:19], v95
	ds_read_b128 v[20:23], v95 offset:64
	s_waitcnt lgkmcnt(1)
	v_mfma_f32_16x16x32_bf16 v[16:19], v[12:15], v[16:19], 0
	v_add_u32_e32 v30, s2, v85
	v_add_u32_e32 v31, s2, v88
	v_add_u32_e32 v58, 1, v31
	s_waitcnt lgkmcnt(0)
	v_mfma_f32_16x16x32_bf16 v[16:19], v[8:11], v[20:23], v[16:19]
	v_add_u32_e32 v20, 0xffffff80, v30
	v_cmp_ge_i32_e32 vcc, v31, v20
	s_and_b64 s[0:1], s[42:43], vcc
	s_and_b64 vcc, s[16:17], s[0:1]
	v_cmp_ge_i32_e64 s[0:1], v58, v20
	s_nop 2
	v_cndmask_b32_e32 v29, v93, v16, vcc
	v_cmp_gt_i32_e32 vcc, v30, v58
	s_and_b64 s[0:1], vcc, s[0:1]
	s_and_b64 vcc, s[16:17], s[0:1]
	v_add_u32_e32 v59, 2, v31
	ds_read_b128 v[96:99], v95 offset:2304
	ds_read_b128 v[100:103], v95 offset:2368
	v_cndmask_b32_e32 v22, v93, v17, vcc
	v_cmp_gt_i32_e32 vcc, v30, v59
	v_cmp_ge_i32_e64 s[0:1], v59, v20
	s_and_b64 s[0:1], vcc, s[0:1]
	s_and_b64 vcc, s[16:17], s[0:1]
	v_add_u32_e32 v60, 3, v31
	v_cndmask_b32_e32 v18, v93, v18, vcc
	v_cmp_gt_i32_e32 vcc, v30, v60
	v_cmp_ge_i32_e64 s[0:1], v60, v20
	s_waitcnt lgkmcnt(1)
	v_mfma_f32_16x16x32_bf16 v[96:99], v[12:15], v[96:99], 0
	s_and_b64 s[0:1], vcc, s[0:1]
	s_add_i32 s6, s4, s2
	s_and_b64 vcc, s[16:17], s[0:1]
	s_add_i32 s0, s6, 16
	s_cmpk_gt_u32 s0, 0x7f
	v_cndmask_b32_e32 v16, v93, v19, vcc
	v_add_u32_e32 v17, 16, v30
	s_waitcnt lgkmcnt(0)
	v_mfma_f32_16x16x32_bf16 v[96:99], v[8:11], v[100:103], v[96:99]
	v_add_u32_e32 v19, 0xffffff90, v30
	s_cselect_b64 s[0:1], -1, 0
	s_or_b64 s[10:11], s[16:17], s[0:1]
	v_cmp_gt_i32_e32 vcc, v17, v31
	v_cmp_ge_i32_e64 s[0:1], v31, v19
	s_and_b64 s[0:1], vcc, s[0:1]
	s_and_b64 vcc, s[0:1], s[10:11]
	s_nop 0
	v_cndmask_b32_e32 v96, v93, v96, vcc
	v_cmp_gt_i32_e32 vcc, v17, v58
	v_cmp_ge_i32_e64 s[0:1], v58, v19
	s_and_b64 s[0:1], vcc, s[0:1]
	s_and_b64 vcc, s[0:1], s[10:11]
	v_cndmask_b32_e32 v26, v93, v97, vcc
	v_cmp_gt_i32_e32 vcc, v17, v59
	v_cmp_ge_i32_e64 s[0:1], v59, v19
	s_and_b64 s[0:1], vcc, s[0:1]
	s_and_b64 vcc, s[0:1], s[10:11]
	v_cndmask_b32_e32 v20, v93, v98, vcc
	v_cmp_gt_i32_e32 vcc, v17, v60
	v_cmp_ge_i32_e64 s[0:1], v60, v19
	s_and_b64 s[0:1], vcc, s[0:1]
	s_and_b64 vcc, s[0:1], s[10:11]
	v_cndmask_b32_e32 v17, v93, v99, vcc
	ds_read_b128 v[98:101], v95 offset:4608
	ds_read_b128 v[108:111], v95 offset:4672
	s_waitcnt lgkmcnt(1)
	v_mfma_f32_16x16x32_bf16 v[98:101], v[12:15], v[98:101], 0
	s_add_i32 s0, s6, 32
	s_cmpk_gt_u32 s0, 0x7f
	v_add_u32_e32 v19, 32, v30
	s_waitcnt lgkmcnt(0)
	v_mfma_f32_16x16x32_bf16 v[100:103], v[8:11], v[108:111], v[98:101]
	v_add_u32_e32 v21, 0xffffffa0, v30
	s_cselect_b64 s[0:1], -1, 0
	s_or_b64 s[10:11], s[16:17], s[0:1]
	v_cmp_gt_i32_e32 vcc, v19, v31
	v_cmp_ge_i32_e64 s[0:1], v31, v21
	s_and_b64 s[0:1], vcc, s[0:1]
	s_and_b64 vcc, s[0:1], s[10:11]
	s_nop 0
	v_cndmask_b32_e32 v100, v93, v100, vcc
	v_cmp_gt_i32_e32 vcc, v19, v58
	v_cmp_ge_i32_e64 s[0:1], v58, v21
	s_and_b64 s[0:1], vcc, s[0:1]
	s_and_b64 vcc, s[0:1], s[10:11]
	ds_read_b128 v[108:111], v95 offset:6912
	ds_read_b128 v[112:115], v95 offset:6976
	v_cndmask_b32_e32 v56, v93, v101, vcc
	v_cmp_gt_i32_e32 vcc, v19, v59
	v_cmp_ge_i32_e64 s[0:1], v59, v21
	s_and_b64 s[0:1], vcc, s[0:1]
	s_and_b64 vcc, s[0:1], s[10:11]
	v_cndmask_b32_e32 v23, v93, v102, vcc
	v_cmp_gt_i32_e32 vcc, v19, v60
	v_cmp_ge_i32_e64 s[0:1], v60, v21
	s_waitcnt lgkmcnt(1)
	v_mfma_f32_16x16x32_bf16 v[108:111], v[12:15], v[108:111], 0
	s_and_b64 s[0:1], vcc, s[0:1]
	s_and_b64 vcc, s[0:1], s[10:11]
	s_add_i32 s0, s6, 48
	s_cmpk_gt_u32 s0, 0x7f
	v_add_u32_e32 v21, 48, v30
	s_waitcnt lgkmcnt(0)
	v_mfma_f32_16x16x32_bf16 v[108:111], v[8:11], v[112:115], v[108:111]
	v_add_u32_e32 v25, 0xffffffb0, v30
	s_cselect_b64 s[0:1], -1, 0
	v_cndmask_b32_e32 v19, v93, v103, vcc
	s_or_b64 s[10:11], s[16:17], s[0:1]
	v_cmp_gt_i32_e32 vcc, v21, v31
	v_cmp_ge_i32_e64 s[0:1], v31, v25
	s_and_b64 s[0:1], vcc, s[0:1]
	s_and_b64 vcc, s[0:1], s[10:11]
	v_cndmask_b32_e32 v103, v93, v108, vcc
	v_cmp_gt_i32_e32 vcc, v21, v58
	v_cmp_ge_i32_e64 s[0:1], v58, v25
	s_and_b64 s[0:1], vcc, s[0:1]
	s_and_b64 vcc, s[0:1], s[10:11]
	v_cndmask_b32_e32 v97, v93, v109, vcc
	v_cmp_gt_i32_e32 vcc, v21, v59
	v_cmp_ge_i32_e64 s[0:1], v59, v25
	s_and_b64 s[0:1], vcc, s[0:1]
	s_and_b64 vcc, s[0:1], s[10:11]
	v_cndmask_b32_e32 v27, v93, v110, vcc
	v_cmp_gt_i32_e32 vcc, v21, v60
	v_cmp_ge_i32_e64 s[0:1], v60, v25
	s_and_b64 s[0:1], vcc, s[0:1]
	s_and_b64 vcc, s[0:1], s[10:11]
	v_cndmask_b32_e32 v21, v93, v111, vcc
	ds_read_b128 v[108:111], v95 offset:9216
	ds_read_b128 v[112:115], v95 offset:9280
	s_waitcnt lgkmcnt(1)
; __device__ __forceinline__ void attn_unit(const AtArgs& A, unsigned char* lds, int unit, int tid, int wave, int lane) {
;     ...
; #pragma unroll
;         for (int kt = 0; kt < 9; ++kt) {
;             const int key = (q0 / 16 + kt) * 16 + fr;
;             const bf16x8 kb0 = *(const bf16x8*)(KS + key * KST + fq * 8), kb1 = *(const bf16x8*)(KS + key * KST + 32 + fq * 8);
;             f32x4 a = (f32x4){0.f, 0.f, 0.f, 0.f};
;             a = __builtin_amdgcn_mfma_f32_16x16x32_bf16(qa0, kb0, a, 0, 0, 0); a = __builtin_amdgcn_mfma_f32_16x16x32_bf16(qa1, kb1, a, 0, 0, 0);
; #pragma unroll
;             for (int r = 0; r < 4; ++r) {
;                 const int qi = q0 + fq * 4 + r;
;                 const bool ok = (key > qi) && (key <= qi + 128) && (nb > 0 || key >= 128);
;                 a[r] = ok ? a[r] : -1e30f;
;             }
;             sc[kt] = a;
;         }
	v_mfma_f32_16x16x32_bf16 v[108:111], v[12:15], v[108:111], 0
	s_add_i32 s0, s6, 64
	s_cmpk_gt_u32 s0, 0x7f
	v_add_u32_e32 v25, 64, v30
	s_waitcnt lgkmcnt(0)
	v_mfma_f32_16x16x32_bf16 v[108:111], v[8:11], v[112:115], v[108:111]
	v_subrev_u32_e32 v28, 64, v30
	s_cselect_b64 s[0:1], -1, 0
	s_or_b64 s[10:11], s[16:17], s[0:1]
	v_cmp_gt_i32_e32 vcc, v25, v31
	v_cmp_ge_i32_e64 s[0:1], v31, v28
	s_and_b64 s[0:1], vcc, s[0:1]
	s_and_b64 vcc, s[0:1], s[10:11]
	s_nop 0
	v_cndmask_b32_e32 v116, v93, v108, vcc
	v_cmp_gt_i32_e32 vcc, v25, v58
	v_cmp_ge_i32_e64 s[0:1], v58, v28
	s_and_b64 s[0:1], vcc, s[0:1]
	s_and_b64 vcc, s[0:1], s[10:11]
	v_cndmask_b32_e32 v101, v93, v109, vcc
	v_cmp_gt_i32_e32 vcc, v25, v59
	v_cmp_ge_i32_e64 s[0:1], v59, v28
	s_and_b64 s[0:1], vcc, s[0:1]
	s_and_b64 vcc, s[0:1], s[10:11]
	v_cndmask_b32_e32 v57, v93, v110, vcc
	v_cmp_gt_i32_e32 vcc, v25, v60
	v_cmp_ge_i32_e64 s[0:1], v60, v28
	s_and_b64 s[0:1], vcc, s[0:1]
	s_and_b64 vcc, s[0:1], s[10:11]
	v_cndmask_b32_e32 v25, v93, v111, vcc
	ds_read_b128 v[108:111], v95 offset:11520
	ds_read_b128 v[112:115], v95 offset:11584
	s_waitcnt lgkmcnt(1)
	v_mfma_f32_16x16x32_bf16 v[108:111], v[12:15], v[108:111], 0
	s_add_i32 s0, s6, 0x50
	s_cmpk_gt_u32 s0, 0x7f
	v_add_u32_e32 v28, 0x50, v30
	s_waitcnt lgkmcnt(0)
	v_mfma_f32_16x16x32_bf16 v[108:111], v[8:11], v[112:115], v[108:111]
	v_subrev_u32_e32 v61, 48, v30
	s_cselect_b64 s[0:1], -1, 0
	s_or_b64 s[10:11], s[16:17], s[0:1]
	v_cmp_gt_i32_e32 vcc, v28, v31
	v_cmp_ge_i32_e64 s[0:1], v31, v61
	s_and_b64 s[0:1], vcc, s[0:1]
	s_and_b64 vcc, s[0:1], s[10:11]
	s_nop 0
	v_cndmask_b32_e32 v117, v93, v108, vcc
	v_cmp_gt_i32_e32 vcc, v28, v58
	v_cmp_ge_i32_e64 s[0:1], v58, v61
	s_and_b64 s[0:1], vcc, s[0:1]
	s_and_b64 vcc, s[0:1], s[10:11]
	v_cndmask_b32_e32 v118, v93, v109, vcc
	v_cmp_gt_i32_e32 vcc, v28, v59
	v_cmp_ge_i32_e64 s[0:1], v59, v61
	s_and_b64 s[0:1], vcc, s[0:1]
	s_and_b64 vcc, s[0:1], s[10:11]
	v_cndmask_b32_e32 v98, v93, v110, vcc
	v_cmp_gt_i32_e32 vcc, v28, v60
	v_cmp_ge_i32_e64 s[0:1], v60, v61
	s_and_b64 s[0:1], vcc, s[0:1]
	s_and_b64 vcc, s[0:1], s[10:11]
	v_cndmask_b32_e32 v28, v93, v111, vcc
	ds_read_b128 v[108:111], v95 offset:13824
	ds_read_b128 v[112:115], v95 offset:13888
	s_waitcnt lgkmcnt(1)
	v_mfma_f32_16x16x32_bf16 v[108:111], v[12:15], v[108:111], 0
	s_add_i32 s0, s6, 0x60
	s_cmpk_gt_u32 s0, 0x7f
	v_add_u32_e32 v61, 0x60, v30
	s_waitcnt lgkmcnt(0)
	v_mfma_f32_16x16x32_bf16 v[108:111], v[8:11], v[112:115], v[108:111]
	v_subrev_u32_e32 v99, 32, v30
	s_cselect_b64 s[0:1], -1, 0
	s_or_b64 s[10:11], s[16:17], s[0:1]
	v_cmp_gt_i32_e32 vcc, v61, v31
	v_cmp_ge_i32_e64 s[0:1], v31, v99
	s_and_b64 s[0:1], vcc, s[0:1]
	s_and_b64 vcc, s[0:1], s[10:11]
	s_nop 0
	v_cndmask_b32_e32 v119, v93, v108, vcc
	v_cmp_gt_i32_e32 vcc, v61, v58
	v_cmp_ge_i32_e64 s[0:1], v58, v99
	s_and_b64 s[0:1], vcc, s[0:1]
	s_and_b64 vcc, s[0:1], s[10:11]
	v_cndmask_b32_e32 v120, v93, v109, vcc
	v_cmp_gt_i32_e32 vcc, v61, v59
	v_cmp_ge_i32_e64 s[0:1], v59, v99
	s_and_b64 s[0:1], vcc, s[0:1]
	s_and_b64 vcc, s[0:1], s[10:11]
	v_cndmask_b32_e32 v102, v93, v110, vcc
	v_cmp_gt_i32_e32 vcc, v61, v60
	v_cmp_ge_i32_e64 s[0:1], v60, v99
	s_and_b64 s[0:1], vcc, s[0:1]
	s_and_b64 vcc, s[0:1], s[10:11]
	v_cndmask_b32_e32 v61, v93, v111, vcc
	ds_read_b128 v[108:111], v95 offset:16128
	ds_read_b128 v[112:115], v95 offset:16192
	s_waitcnt lgkmcnt(1)
	v_mfma_f32_16x16x32_bf16 v[108:111], v[12:15], v[108:111], 0
	s_addk_i32 s6, 0x70
	s_cmpk_gt_u32 s6, 0x7f
	v_add_u32_e32 v99, 0x70, v30
	s_waitcnt lgkmcnt(0)
	v_mfma_f32_16x16x32_bf16 v[108:111], v[8:11], v[112:115], v[108:111]
	v_add_u32_e32 v112, -16, v30
	s_cselect_b64 s[0:1], -1, 0
	s_or_b64 s[10:11], s[16:17], s[0:1]
	v_cmp_gt_i32_e32 vcc, v99, v31
	v_cmp_ge_i32_e64 s[0:1], v31, v112
	s_and_b64 s[0:1], vcc, s[0:1]
	s_and_b64 vcc, s[0:1], s[10:11]
	s_nop 0
	v_cndmask_b32_e32 v121, v93, v108, vcc
	v_cmp_gt_i32_e32 vcc, v99, v58
	v_cmp_ge_i32_e64 s[0:1], v58, v112
	s_and_b64 s[0:1], vcc, s[0:1]
	s_and_b64 vcc, s[0:1], s[10:11]
	v_cndmask_b32_e32 v122, v93, v109, vcc
	v_cmp_gt_i32_e32 vcc, v99, v59
	v_cmp_ge_i32_e64 s[0:1], v59, v112
	s_and_b64 s[0:1], vcc, s[0:1]
	s_and_b64 vcc, s[0:1], s[10:11]
	v_cndmask_b32_e32 v123, v93, v110, vcc
	v_cmp_gt_i32_e32 vcc, v99, v60
	v_cmp_ge_i32_e64 s[0:1], v60, v112
	s_and_b64 s[0:1], vcc, s[0:1]
	s_and_b64 vcc, s[0:1], s[10:11]
	v_cndmask_b32_e32 v99, v93, v111, vcc
	ds_read_b128 v[108:111], v95 offset:18432
	ds_read_b128 v[112:115], v95 offset:18496
	s_waitcnt lgkmcnt(1)
	v_mfma_f32_16x16x32_bf16 v[12:15], v[12:15], v[108:111], 0
	v_add_u32_e32 v124, 0x80, v30
	v_cmp_gt_i32_e32 vcc, v124, v31
	v_cmp_ge_i32_e64 s[0:1], v31, v30
	s_waitcnt lgkmcnt(0)
; __device__ __forceinline__ unsigned f2bf(float f) { return pk2(f, f) & 0xffffu; }
; __device__ __forceinline__ float row16_sum(float v) { v += dpp_perm<0xB1, 0xF>(v); v += dpp_perm<0x4E, 0xF>(v); v += dpp_perm<0x141, 0xF>(v); v += dpp_perm<0x140, 0xF>(v); return v; }
; __device__ __forceinline__ float row16_max(float v) { v = fmaxf(v, dpp_perm<0xB1, 0xF>(v)); v = fmaxf(v, dpp_perm<0x4E, 0xF>(v)); v = fmaxf(v, dpp_perm<0x141, 0xF>(v)); v = fmaxf(v, dpp_perm<0x140, 0xF>(v)); return v; }
; __device__ __forceinline__ void attn_unit(const AtArgs& A, unsigned char* lds, int unit, int tid, int wave, int lane) {
;     ...
;             a = __builtin_amdgcn_mfma_f32_16x16x32_bf16(qa0, kb0, a, 0, 0, 0); a = __builtin_amdgcn_mfma_f32_16x16x32_bf16(qa1, kb1, a, 0, 0, 0);
; #pragma unroll
;             for (int r = 0; r < 4; ++r) {
;                 const int qi = q0 + fq * 4 + r;
;                 const bool ok = (key > qi) && (key <= qi + 128) && (nb > 0 || key >= 128);
;                 a[r] = ok ? a[r] : -1e30f;
;             }
;             sc[kt] = a;
;         }
;         float m4[4], s4[4];
; #pragma unroll
;         for (int r = 0; r < 4; ++r) {
;             float m = sc[0][r];
; #pragma unroll
;             for (int kt = 1; kt < 9; ++kt) m = fmaxf(m, sc[kt][r]);
;             m = row16_max(m);
;             m4[r] = fmaxf(m, sink);
;             float s = 0.f;
; #pragma unroll
;             for (int kt = 0; kt < 9; ++kt) { const float e = __expf(sc[kt][r] - m4[r]); sc[kt][r] = e; s += e; }
;             s = row16_sum(s);
;             s4[r] = __builtin_amdgcn_rcpf(s + __expf(sink - m4[r]));
;         }
; #pragma unroll
;         for (int kt = 0; kt < 9; ++kt)
; #pragma unroll
;             for (int r = 0; r < 4; ++r) PS[(fq * 4 + r) * PST + kt * 16 + fr] = (bf16)f2bf(sc[kt][r] * s4[r]);
	v_mfma_f32_16x16x32_bf16 v[8:11], v[8:11], v[112:115], v[12:15]
	s_and_b64 vcc, vcc, s[0:1]
	v_cmp_ge_i32_e64 s[0:1], v58, v30
	v_add_u32_e32 v24, 0x900, v95
	v_mov_b32_e32 v95, 0
	v_mov_b32_e32 v108, 0
	s_nop 2
	v_cndmask_b32_e32 v8, v93, v8, vcc
	v_cmp_gt_i32_e32 vcc, v124, v58
	s_and_b64 vcc, vcc, s[0:1]
	v_cmp_ge_i32_e64 s[0:1], v59, v30
	v_cndmask_b32_e32 v58, v93, v9, vcc
	v_max3_f32 v9, v29, v96, v100
	v_cmp_gt_i32_e32 vcc, v124, v59
	v_max3_f32 v9, v9, v103, v116
	s_and_b64 vcc, vcc, s[0:1]
	v_max3_f32 v9, v9, v117, v119
	v_cndmask_b32_e32 v59, v93, v10, vcc
	v_max3_f32 v9, v9, v121, v8
	v_mov_b32_e32 v10, 0
	v_cmp_ge_i32_e64 s[0:1], v60, v30
	v_cmp_gt_i32_e32 vcc, v124, v60
	v_mov_b32_dpp v10, v9 quad_perm:[1,0,3,2] row_mask:0xf bank_mask:0xf
	v_max_f32_e32 v10, v10, v10
	v_max_f32_e32 v9, v9, v10
	v_mov_b32_e32 v10, 0
	s_and_b64 vcc, vcc, s[0:1]
	v_cndmask_b32_e32 v31, v93, v11, vcc
	v_mov_b32_dpp v10, v9 quad_perm:[2,3,0,1] row_mask:0xf bank_mask:0xf
	v_max_f32_e32 v10, v10, v10
	v_max_f32_e32 v9, v9, v10
	v_mov_b32_e32 v10, 0
	v_mov_b32_e32 v110, 0
	s_add_i32 s2, s2, 16
	v_mov_b32_dpp v10, v9 row_half_mirror row_mask:0xf bank_mask:0xf
	v_max_f32_e32 v10, v10, v10
	v_max_f32_e32 v9, v9, v10
	v_mov_b32_e32 v10, 0
	s_add_i32 s3, s3, 0xb000
	s_nop 0
	v_mov_b32_dpp v10, v9 row_mirror row_mask:0xf bank_mask:0xf
	v_max3_f32 v30, v9, v10, v38
	v_sub_f32_e32 v10, v96, v30
	v_mul_f32_e32 v10, 0x3fb8aa3b, v10
	v_sub_f32_e32 v9, v29, v30
	v_exp_f32_e32 v29, v10
	v_sub_f32_e32 v10, v100, v30
	v_mul_f32_e32 v9, 0x3fb8aa3b, v9
	v_mul_f32_e32 v10, 0x3fb8aa3b, v10
	v_exp_f32_e32 v14, v9
	v_exp_f32_e32 v15, v10
	v_sub_f32_e32 v10, v103, v30
	v_mul_f32_e32 v10, 0x3fb8aa3b, v10
	v_exp_f32_e32 v12, v10
	v_sub_f32_e32 v10, v116, v30
	v_sub_f32_e32 v11, v117, v30
	v_mul_f32_e32 v10, 0x3fb8aa3b, v10
	v_mul_f32_e32 v11, 0x3fb8aa3b, v11
	v_add_f32_e32 v9, 0, v14
	v_exp_f32_e32 v10, v10
	v_exp_f32_e32 v13, v11
	v_sub_f32_e32 v11, v119, v30
	v_add_f32_e32 v9, v29, v9
	v_mul_f32_e32 v11, 0x3fb8aa3b, v11
	v_add_f32_e32 v9, v15, v9
	v_exp_f32_e32 v11, v11
	v_add_f32_e32 v9, v12, v9
	v_add_f32_e32 v9, v10, v9
	v_add_f32_e32 v9, v13, v9
	v_add_f32_e32 v60, v11, v9
	v_sub_f32_e32 v9, v121, v30
	v_mul_f32_e32 v9, 0x3fb8aa3b, v9
	v_sub_f32_e32 v8, v8, v30
	v_exp_f32_e32 v9, v9
	v_mul_f32_e32 v8, 0x3fb8aa3b, v8
	v_exp_f32_e32 v8, v8
	v_sub_f32_e32 v30, v38, v30
	v_add_f32_e32 v60, v9, v60
	v_mul_f32_e32 v30, 0x3fb8aa3b, v30
	v_add_f32_e32 v60, v8, v60
	v_exp_f32_e32 v30, v30
	s_nop 0
	v_add_f32_dpp v60, v60, v60 quad_perm:[1,0,3,2] row_mask:0xf bank_mask:0xf bound_ctrl:1
	s_nop 1
	v_add_f32_dpp v60, v60, v60 quad_perm:[2,3,0,1] row_mask:0xf bank_mask:0xf bound_ctrl:1
	s_nop 1
	v_add_f32_dpp v60, v60, v60 row_half_mirror row_mask:0xf bank_mask:0xf bound_ctrl:1
	s_nop 1
	v_add_f32_dpp v60, v60, v60 row_mirror row_mask:0xf bank_mask:0xf bound_ctrl:1
	v_add_f32_e32 v30, v30, v60
	v_max3_f32 v60, v22, v26, v56
	v_max3_f32 v60, v60, v97, v101
	v_max3_f32 v60, v60, v118, v120
	v_max3_f32 v60, v60, v122, v58
	v_rcp_f32_e32 v30, v30
	s_nop 0
	v_mov_b32_dpp v95, v60 quad_perm:[1,0,3,2] row_mask:0xf bank_mask:0xf
	v_max_f32_e32 v95, v95, v95
	v_max_f32_e32 v60, v60, v95
	v_mov_b32_e32 v95, 0
	v_mul_f32_e32 v14, v14, v30
	v_mul_f32_e32 v10, v10, v30
	v_mov_b32_dpp v95, v60 quad_perm:[2,3,0,1] row_mask:0xf bank_mask:0xf
	v_max_f32_e32 v95, v95, v95
	v_max_f32_e32 v60, v60, v95
	v_mov_b32_e32 v95, 0
	v_cvt_pk_bf16_f32 v14, v14, s0
	v_cvt_pk_bf16_f32 v10, v10, s0
	v_mov_b32_dpp v95, v60 row_half_mirror row_mask:0xf bank_mask:0xf
	v_max_f32_e32 v95, v95, v95
	v_max_f32_e32 v60, v60, v95
	v_mov_b32_e32 v95, 0
	ds_write_b16 v79, v14
	ds_write_b16 v79, v10 offset:128
	v_mov_b32_dpp v95, v60 row_mirror row_mask:0xf bank_mask:0xf
	v_max3_f32 v60, v60, v95, v38
	v_sub_f32_e32 v22, v22, v60
	v_mul_f32_e32 v22, 0x3fb8aa3b, v22
	v_sub_f32_e32 v26, v26, v60
	v_exp_f32_e32 v22, v22
	v_mul_f32_e32 v26, 0x3fb8aa3b, v26
	v_sub_f32_e32 v56, v56, v60
	v_exp_f32_e32 v26, v26
	v_mul_f32_e32 v56, 0x3fb8aa3b, v56
	v_sub_f32_e32 v96, v97, v60
	v_exp_f32_e32 v56, v56
	v_mul_f32_e32 v96, 0x3fb8aa3b, v96
	v_sub_f32_e32 v97, v101, v60
	v_exp_f32_e32 v96, v96
	v_mul_f32_e32 v97, 0x3fb8aa3b, v97
	v_sub_f32_e32 v100, v118, v60
	v_add_f32_e32 v95, 0, v22
	v_exp_f32_e32 v97, v97
	v_mul_f32_e32 v100, 0x3fb8aa3b, v100
	v_sub_f32_e32 v101, v120, v60
	v_add_f32_e32 v95, v26, v95
	v_exp_f32_e32 v100, v100
	v_mul_f32_e32 v101, 0x3fb8aa3b, v101
	v_sub_f32_e32 v103, v122, v60
	v_add_f32_e32 v95, v56, v95
	v_exp_f32_e32 v101, v101
	v_mul_f32_e32 v103, 0x3fb8aa3b, v103
	v_sub_f32_e32 v58, v58, v60
	v_add_f32_e32 v95, v96, v95
	v_exp_f32_e32 v103, v103
	v_mul_f32_e32 v58, 0x3fb8aa3b, v58
	v_add_f32_e32 v95, v97, v95
	v_exp_f32_e32 v58, v58
	v_add_f32_e32 v95, v100, v95
	v_add_f32_e32 v95, v101, v95
	v_add_f32_e32 v95, v103, v95
	v_sub_f32_e32 v60, v38, v60
	v_add_f32_e32 v95, v58, v95
	v_mul_f32_e32 v60, 0x3fb8aa3b, v60
	v_exp_f32_e32 v60, v60
	v_add_f32_dpp v95, v95, v95 quad_perm:[1,0,3,2] row_mask:0xf bank_mask:0xf bound_ctrl:1
	v_mul_f32_e32 v12, v12, v30
	v_mul_f32_e32 v9, v9, v30
	v_add_f32_dpp v95, v95, v95 quad_perm:[2,3,0,1] row_mask:0xf bank_mask:0xf bound_ctrl:1
	v_mul_f32_e32 v8, v8, v30
	v_cvt_pk_bf16_f32 v12, v12, s0
	v_add_f32_dpp v95, v95, v95 row_half_mirror row_mask:0xf bank_mask:0xf bound_ctrl:1
	v_cvt_pk_bf16_f32 v9, v9, s0
	v_cvt_pk_bf16_f32 v8, v8, s0
	v_add_f32_dpp v95, v95, v95 row_mirror row_mask:0xf bank_mask:0xf bound_ctrl:1
	v_add_f32_e32 v60, v60, v95
	v_max3_f32 v95, v18, v20, v23
	v_max3_f32 v95, v95, v27, v57
	v_max3_f32 v95, v95, v98, v102
	v_max3_f32 v95, v95, v123, v59
; __device__ __forceinline__ unsigned f2bf(float f) { return pk2(f, f) & 0xffffu; }
; __device__ __forceinline__ float row16_sum(float v) { v += dpp_perm<0xB1, 0xF>(v); v += dpp_perm<0x4E, 0xF>(v); v += dpp_perm<0x141, 0xF>(v); v += dpp_perm<0x140, 0xF>(v); return v; }
; __device__ __forceinline__ float row16_max(float v) { v = fmaxf(v, dpp_perm<0xB1, 0xF>(v)); v = fmaxf(v, dpp_perm<0x4E, 0xF>(v)); v = fmaxf(v, dpp_perm<0x141, 0xF>(v)); v = fmaxf(v, dpp_perm<0x140, 0xF>(v)); return v; }
; __device__ __forceinline__ void attn_unit(const AtArgs& A, unsigned char* lds, int unit, int tid, int wave, int lane) {
;     ...
;         float m4[4], s4[4];
; #pragma unroll
;         for (int r = 0; r < 4; ++r) {
;             float m = sc[0][r];
; #pragma unroll
;             for (int kt = 1; kt < 9; ++kt) m = fmaxf(m, sc[kt][r]);
;             m = row16_max(m);
;             m4[r] = fmaxf(m, sink);
;             float s = 0.f;
; #pragma unroll
;             for (int kt = 0; kt < 9; ++kt) { const float e = __expf(sc[kt][r] - m4[r]); sc[kt][r] = e; s += e; }
;             s = row16_sum(s);
;             s4[r] = __builtin_amdgcn_rcpf(s + __expf(sink - m4[r]));
;         }
; #pragma unroll
;         for (int kt = 0; kt < 9; ++kt)
; #pragma unroll
;             for (int r = 0; r < 4; ++r) PS[(fq * 4 + r) * PST + kt * 16 + fr] = (bf16)f2bf(sc[kt][r] * s4[r]);
	v_rcp_f32_e32 v60, v60
	ds_write_b16 v79, v12 offset:96
	v_mov_b32_dpp v108, v95 quad_perm:[1,0,3,2] row_mask:0xf bank_mask:0xf
	v_max_f32_e32 v108, v108, v108
	v_max_f32_e32 v95, v95, v108
	v_mov_b32_e32 v108, 0
	v_mul_f32_e32 v14, v22, v60
	v_mul_f32_e32 v10, v97, v60
	v_mov_b32_dpp v108, v95 quad_perm:[2,3,0,1] row_mask:0xf bank_mask:0xf
	v_max_f32_e32 v108, v108, v108
	v_max_f32_e32 v95, v95, v108
	v_mov_b32_e32 v108, 0
	v_cvt_pk_bf16_f32 v14, v14, s0
	v_cvt_pk_bf16_f32 v10, v10, s0
	v_mov_b32_dpp v108, v95 row_half_mirror row_mask:0xf bank_mask:0xf
	v_max_f32_e32 v108, v108, v108
	v_max_f32_e32 v95, v95, v108
	v_mov_b32_e32 v108, 0
	ds_write_b16 v79, v14 offset:336
	ds_write_b16 v79, v10 offset:464
	v_mov_b32_dpp v108, v95 row_mirror row_mask:0xf bank_mask:0xf
	v_max3_f32 v95, v95, v108, v38
	v_sub_f32_e32 v18, v18, v95
	v_mul_f32_e32 v18, 0x3fb8aa3b, v18
	v_sub_f32_e32 v20, v20, v95
	v_exp_f32_e32 v18, v18
	v_mul_f32_e32 v20, 0x3fb8aa3b, v20
	v_sub_f32_e32 v23, v23, v95
	v_exp_f32_e32 v20, v20
	v_mul_f32_e32 v23, 0x3fb8aa3b, v23
	v_sub_f32_e32 v27, v27, v95
	v_exp_f32_e32 v23, v23
	v_mul_f32_e32 v27, 0x3fb8aa3b, v27
	v_sub_f32_e32 v57, v57, v95
	v_exp_f32_e32 v27, v27
	v_mul_f32_e32 v57, 0x3fb8aa3b, v57
	v_sub_f32_e32 v98, v98, v95
	v_add_f32_e32 v108, 0, v18
	v_exp_f32_e32 v57, v57
	v_mul_f32_e32 v98, 0x3fb8aa3b, v98
	v_sub_f32_e32 v102, v102, v95
	v_add_f32_e32 v108, v20, v108
	v_exp_f32_e32 v98, v98
	v_mul_f32_e32 v102, 0x3fb8aa3b, v102
	v_sub_f32_e32 v109, v123, v95
	v_add_f32_e32 v108, v23, v108
	v_exp_f32_e32 v102, v102
	v_mul_f32_e32 v109, 0x3fb8aa3b, v109
	v_sub_f32_e32 v59, v59, v95
	v_add_f32_e32 v108, v27, v108
	v_exp_f32_e32 v109, v109
	v_mul_f32_e32 v59, 0x3fb8aa3b, v59
	v_add_f32_e32 v108, v57, v108
	v_exp_f32_e32 v59, v59
	v_add_f32_e32 v108, v98, v108
	v_add_f32_e32 v108, v102, v108
	v_add_f32_e32 v108, v109, v108
	v_sub_f32_e32 v95, v38, v95
	v_add_f32_e32 v108, v59, v108
	v_mul_f32_e32 v95, 0x3fb8aa3b, v95
	v_exp_f32_e32 v95, v95
	v_add_f32_dpp v108, v108, v108 quad_perm:[1,0,3,2] row_mask:0xf bank_mask:0xf bound_ctrl:1
	v_mul_f32_e32 v12, v96, v60
	ds_write_b16 v79, v9 offset:224
	v_add_f32_dpp v108, v108, v108 quad_perm:[2,3,0,1] row_mask:0xf bank_mask:0xf bound_ctrl:1
	v_mul_f32_e32 v9, v103, v60
	ds_write_b16 v79, v8 offset:256
	v_add_f32_dpp v108, v108, v108 row_half_mirror row_mask:0xf bank_mask:0xf bound_ctrl:1
	v_mul_f32_e32 v8, v58, v60
	v_cvt_pk_bf16_f32 v12, v12, s0
	v_add_f32_dpp v108, v108, v108 row_mirror row_mask:0xf bank_mask:0xf bound_ctrl:1
	v_add_f32_e32 v95, v95, v108
	v_max3_f32 v108, v16, v17, v19
	v_max3_f32 v108, v108, v21, v25
	v_max3_f32 v108, v108, v28, v61
	v_max3_f32 v108, v108, v99, v31
	v_rcp_f32_e32 v95, v95
	v_cvt_pk_bf16_f32 v9, v9, s0
	v_mov_b32_dpp v110, v108 quad_perm:[1,0,3,2] row_mask:0xf bank_mask:0xf
	v_max_f32_e32 v110, v110, v110
	v_max_f32_e32 v108, v108, v110
	v_mov_b32_e32 v110, 0
	v_mul_f32_e32 v14, v18, v95
	v_mul_f32_e32 v10, v57, v95
	v_mov_b32_dpp v110, v108 quad_perm:[2,3,0,1] row_mask:0xf bank_mask:0xf
	v_max_f32_e32 v110, v110, v110
	v_max_f32_e32 v108, v108, v110
	v_mov_b32_e32 v110, 0
	v_cvt_pk_bf16_f32 v14, v14, s0
	v_cvt_pk_bf16_f32 v10, v10, s0
	v_mov_b32_dpp v110, v108 row_half_mirror row_mask:0xf bank_mask:0xf
	v_max_f32_e32 v110, v110, v110
	v_max_f32_e32 v108, v108, v110
	v_mov_b32_e32 v110, 0
	ds_write_b16 v79, v14 offset:672
	ds_write_b16 v79, v10 offset:800
	v_mov_b32_dpp v110, v108 row_mirror row_mask:0xf bank_mask:0xf
	v_max3_f32 v108, v108, v110, v38
	v_sub_f32_e32 v16, v16, v108
	v_mul_f32_e32 v16, 0x3fb8aa3b, v16
	v_sub_f32_e32 v17, v17, v108
	v_exp_f32_e32 v16, v16
	v_mul_f32_e32 v17, 0x3fb8aa3b, v17
	v_sub_f32_e32 v19, v19, v108
	v_exp_f32_e32 v17, v17
	v_mul_f32_e32 v19, 0x3fb8aa3b, v19
	v_sub_f32_e32 v21, v21, v108
	v_exp_f32_e32 v19, v19
	v_mul_f32_e32 v21, 0x3fb8aa3b, v21
	v_sub_f32_e32 v25, v25, v108
	v_exp_f32_e32 v21, v21
	v_mul_f32_e32 v25, 0x3fb8aa3b, v25
	v_sub_f32_e32 v28, v28, v108
	v_add_f32_e32 v110, 0, v16
	v_exp_f32_e32 v25, v25
	v_mul_f32_e32 v28, 0x3fb8aa3b, v28
	v_sub_f32_e32 v61, v61, v108
	v_add_f32_e32 v110, v17, v110
	v_exp_f32_e32 v28, v28
	v_mul_f32_e32 v61, 0x3fb8aa3b, v61
	v_sub_f32_e32 v99, v99, v108
	v_add_f32_e32 v110, v19, v110
	v_exp_f32_e32 v61, v61
	v_mul_f32_e32 v99, 0x3fb8aa3b, v99
	v_sub_f32_e32 v31, v31, v108
	v_add_f32_e32 v110, v21, v110
	v_exp_f32_e32 v99, v99
	v_mul_f32_e32 v31, 0x3fb8aa3b, v31
	v_add_f32_e32 v110, v25, v110
	v_exp_f32_e32 v31, v31
	v_add_f32_e32 v110, v28, v110
	v_add_f32_e32 v110, v61, v110
	v_add_f32_e32 v110, v99, v110
	v_sub_f32_e32 v108, v38, v108
	v_add_f32_e32 v110, v31, v110
	v_mul_f32_e32 v108, 0x3fb8aa3b, v108
	v_exp_f32_e32 v108, v108
	v_add_f32_dpp v110, v110, v110 quad_perm:[1,0,3,2] row_mask:0xf bank_mask:0xf bound_ctrl:1
	v_cvt_pk_bf16_f32 v8, v8, s0
	ds_write_b16 v79, v12 offset:432
	v_add_f32_dpp v110, v110, v110 quad_perm:[2,3,0,1] row_mask:0xf bank_mask:0xf bound_ctrl:1
	v_mul_f32_e32 v12, v27, v95
	ds_write_b16 v79, v9 offset:560
	v_add_f32_dpp v110, v110, v110 row_half_mirror row_mask:0xf bank_mask:0xf bound_ctrl:1
	v_mul_f32_e32 v9, v109, v95
	ds_write_b16 v79, v8 offset:592
	v_add_f32_dpp v110, v110, v110 row_mirror row_mask:0xf bank_mask:0xf bound_ctrl:1
	v_add_f32_e32 v108, v108, v110
	v_rcp_f32_e32 v108, v108
	v_mul_f32_e32 v8, v59, v95
	v_cvt_pk_bf16_f32 v12, v12, s0
	v_cvt_pk_bf16_f32 v9, v9, s0
	v_mul_f32_e32 v14, v16, v108
	v_mul_f32_e32 v10, v25, v108
	v_cvt_pk_bf16_f32 v14, v14, s0
	v_cvt_pk_bf16_f32 v10, v10, s0
	ds_write_b16 v79, v14 offset:1008
	v_mul_f32_e32 v14, v29, v30
	ds_write_b16 v79, v10 offset:1136
	v_mul_f32_e32 v10, v13, v30
; __device__ __forceinline__ unsigned f2bf(float f) { return pk2(f, f) & 0xffffu; }
; #define LDS_WAIT() asm volatile("s_waitcnt lgkmcnt(0)" ::: "memory")
; __device__ __forceinline__ void attn_unit(const AtArgs& A, unsigned char* lds, int unit, int tid, int wave, int lane) {
;     ...
; #pragma unroll
;         for (int kt = 0; kt < 9; ++kt)
; #pragma unroll
;             for (int r = 0; r < 4; ++r) PS[(fq * 4 + r) * PST + kt * 16 + fr] = (bf16)f2bf(sc[kt][r] * s4[r]);
; #pragma unroll
;         for (int r = 0; r < 4; ++r) PS[(fq * 4 + r) * PST + 144 + fr] = 0;
;         LDS_WAIT();
;         f32x4 o[4];
; #pragma unroll
;         for (int dt = 0; dt < 4; ++dt) o[dt] = (f32x4){0.f, 0.f, 0.f, 0.f};
; #pragma unroll
;         for (int ks = 0; ks < 5; ++ks) {
;             const bf16x8 pa = *(const bf16x8*)(PS + fr * PST + ks * 32 + fq * 8);
; #pragma unroll
;             for (int dt = 0; dt < 4; ++dt) {
;                 const bf16x8 vb = *(const bf16x8*)(VT + (dt * 16 + fr) * VST + (((((q0 + ks * 32) >> 3) + fq) ^ ((dt * 2 + (fr >> 3)) & 7)) << 3));
;                 o[dt] = __builtin_amdgcn_mfma_f32_16x16x32_bf16(pa, vb, o[dt], 0, 0, 0);
;             }
;         }
	v_cvt_pk_bf16_f32 v14, v14, s0
	v_cvt_pk_bf16_f32 v10, v10, s0
	ds_write_b16 v79, v14 offset:32
	v_mul_f32_e32 v14, v26, v60
	ds_write_b16 v79, v10 offset:160
	v_mul_f32_e32 v10, v100, v60
	v_cvt_pk_bf16_f32 v14, v14, s0
	v_cvt_pk_bf16_f32 v10, v10, s0
	ds_write_b16 v79, v14 offset:368
	v_mul_f32_e32 v14, v20, v95
	ds_write_b16 v79, v10 offset:496
	v_mul_f32_e32 v10, v98, v95
	v_cvt_pk_bf16_f32 v14, v14, s0
	v_cvt_pk_bf16_f32 v10, v10, s0
	ds_write_b16 v79, v14 offset:704
	v_mul_f32_e32 v14, v17, v108
	ds_write_b16 v79, v10 offset:832
	v_mul_f32_e32 v10, v28, v108
	v_cvt_pk_bf16_f32 v14, v14, s0
	v_cvt_pk_bf16_f32 v10, v10, s0
	ds_write_b16 v79, v14 offset:1040
	v_mul_f32_e32 v14, v15, v30
	ds_write_b16 v79, v10 offset:1168
	v_mul_f32_e32 v10, v11, v30
	v_cvt_pk_bf16_f32 v14, v14, s0
	v_cvt_pk_bf16_f32 v10, v10, s0
	ds_write_b16 v79, v14 offset:64
	v_mul_f32_e32 v14, v56, v60
	ds_write_b16 v79, v10 offset:192
	v_mul_f32_e32 v10, v101, v60
	v_cvt_pk_bf16_f32 v14, v14, s0
	v_cvt_pk_bf16_f32 v10, v10, s0
	ds_write_b16 v79, v14 offset:400
	v_mul_f32_e32 v14, v23, v95
	ds_write_b16 v79, v10 offset:528
	v_mul_f32_e32 v10, v102, v95
	v_cvt_pk_bf16_f32 v14, v14, s0
	v_cvt_pk_bf16_f32 v10, v10, s0
	v_cvt_pk_bf16_f32 v8, v8, s0
	ds_write_b16 v79, v14 offset:736
	v_mul_f32_e32 v14, v19, v108
	ds_write_b16 v79, v12 offset:768
	v_mul_f32_e32 v12, v21, v108
	ds_write_b16 v79, v10 offset:864
	v_mul_f32_e32 v10, v61, v108
	ds_write_b16 v79, v9 offset:896
	v_mul_f32_e32 v9, v99, v108
	ds_write_b16 v79, v8 offset:928
	v_mul_f32_e32 v8, v31, v108
	v_cvt_pk_bf16_f32 v14, v14, s0
	v_cvt_pk_bf16_f32 v12, v12, s0
	v_cvt_pk_bf16_f32 v10, v10, s0
	v_cvt_pk_bf16_f32 v9, v9, s0
	v_cvt_pk_bf16_f32 v8, v8, s0
	ds_write_b16 v79, v14 offset:1072
	ds_write_b16 v79, v12 offset:1104
	ds_write_b16 v79, v10 offset:1200
	ds_write_b16 v79, v9 offset:1232
	ds_write_b16 v79, v8 offset:1264
	ds_write_b16 v79, v39 offset:288
	ds_write_b16 v79, v39 offset:624
	ds_write_b16 v79, v39 offset:960
	ds_write_b16 v79, v39 offset:1296
	s_waitcnt lgkmcnt(0)
	ds_read_b128 v[8:11], v77
	v_add_u32_e32 v25, -8, v94
	v_xor_b32_e32 v12, v25, v78
	v_xor_b32_e32 v16, v25, v82
	v_xor_b32_e32 v20, v25, v83
	v_xor_b32_e32 v25, v25, v84
	v_lshl_add_u32 v12, v12, 4, v80
	v_lshl_add_u32 v16, v16, 4, v80
	v_lshl_add_u32 v20, v20, 4, v80
	v_lshl_add_u32 v25, v25, 4, v81
	ds_read_b128 v[12:15], v12 offset:36864
	ds_read_b128 v[16:19], v16 offset:47872
	ds_read_b128 v[20:23], v20 offset:58880
	ds_read_b128 v[26:29], v25 offset:33024
	v_add_u32_e32 v25, -4, v94
	v_xor_b32_e32 v30, v25, v78
	v_lshl_add_u32 v30, v30, 4, v80
	ds_read_b128 v[56:59], v30 offset:36864
	s_waitcnt lgkmcnt(4)
	v_mfma_f32_16x16x32_bf16 v[12:15], v[8:11], v[12:15], 0
	v_xor_b32_e32 v30, v25, v82
	v_lshl_add_u32 v30, v30, 4, v80
	v_mov_b32_e32 v95, v24
	s_waitcnt lgkmcnt(3)
	v_mfma_f32_16x16x32_bf16 v[16:19], v[8:11], v[16:19], 0
	s_waitcnt lgkmcnt(2)
	v_mfma_f32_16x16x32_bf16 v[20:23], v[8:11], v[20:23], 0
	s_waitcnt lgkmcnt(1)
	v_mfma_f32_16x16x32_bf16 v[8:11], v[8:11], v[26:29], 0
	ds_read_b128 v[26:29], v77 offset:64
	s_waitcnt lgkmcnt(0)
	v_mfma_f32_16x16x32_bf16 v[12:15], v[26:29], v[56:59], v[12:15]
	ds_read_b128 v[56:59], v30 offset:47872
	v_xor_b32_e32 v30, v25, v83
	v_lshl_add_u32 v30, v30, 4, v80
	s_waitcnt lgkmcnt(0)
	v_mfma_f32_16x16x32_bf16 v[16:19], v[26:29], v[56:59], v[16:19]
	ds_read_b128 v[56:59], v30 offset:58880
	v_xor_b32_e32 v25, v25, v84
	v_lshl_add_u32 v25, v25, 4, v81
	s_waitcnt lgkmcnt(0)
	v_mfma_f32_16x16x32_bf16 v[20:23], v[26:29], v[56:59], v[20:23]
	ds_read_b128 v[56:59], v25 offset:33024
	v_xor_b32_e32 v25, v94, v78
	v_lshl_add_u32 v25, v25, 4, v80
	s_waitcnt lgkmcnt(0)
	v_mfma_f32_16x16x32_bf16 v[8:11], v[26:29], v[56:59], v[8:11]
	ds_read_b128 v[26:29], v77 offset:128
	ds_read_b128 v[56:59], v25 offset:36864
	v_xor_b32_e32 v25, v94, v82
	v_lshl_add_u32 v25, v25, 4, v80
	s_waitcnt lgkmcnt(0)
	v_mfma_f32_16x16x32_bf16 v[12:15], v[26:29], v[56:59], v[12:15]
	ds_read_b128 v[56:59], v25 offset:47872
	v_xor_b32_e32 v25, v94, v83
	v_lshl_add_u32 v25, v25, 4, v80
	s_waitcnt lgkmcnt(0)
	v_mfma_f32_16x16x32_bf16 v[16:19], v[26:29], v[56:59], v[16:19]
	ds_read_b128 v[56:59], v25 offset:58880
	v_add_u32_e32 v25, 4, v94
	s_waitcnt lgkmcnt(0)
	v_mfma_f32_16x16x32_bf16 v[56:59], v[26:29], v[56:59], v[20:23]
	s_nop 2
	v_xor_b32_e32 v20, v94, v84
	v_lshl_add_u32 v20, v20, 4, v81
	ds_read_b128 v[20:23], v20 offset:33024
	s_waitcnt lgkmcnt(0)
	v_mfma_f32_16x16x32_bf16 v[8:11], v[26:29], v[20:23], v[8:11]
	ds_read_b128 v[26:29], v77 offset:192
	v_xor_b32_e32 v20, v25, v78
	v_lshl_add_u32 v20, v20, 4, v80
	ds_read_b128 v[20:23], v20 offset:36864
	s_waitcnt lgkmcnt(0)
	v_mfma_f32_16x16x32_bf16 v[20:23], v[26:29], v[20:23], v[12:15]
	s_nop 2
	v_xor_b32_e32 v12, v25, v82
	v_lshl_add_u32 v12, v12, 4, v80
	ds_read_b128 v[12:15], v12 offset:47872
	s_waitcnt lgkmcnt(0)
	v_mfma_f32_16x16x32_bf16 v[16:19], v[26:29], v[12:15], v[16:19]
	v_xor_b32_e32 v12, v25, v83
	v_lshl_add_u32 v12, v12, 4, v80
	ds_read_b128 v[12:15], v12 offset:58880
	v_xor_b32_e32 v25, v25, v84
	v_lshl_add_u32 v25, v25, 4, v81
	s_waitcnt lgkmcnt(0)
	v_mfma_f32_16x16x32_bf16 v[12:15], v[26:29], v[12:15], v[56:59]
	s_nop 2
	ds_read_b128 v[56:59], v25 offset:33024
	v_add_u32_e32 v25, 8, v94
	s_waitcnt lgkmcnt(0)
	v_mfma_f32_16x16x32_bf16 v[8:11], v[26:29], v[56:59], v[8:11]
	ds_read_b128 v[26:29], v77 offset:256
	v_xor_b32_e32 v30, v25, v78
	v_lshl_add_u32 v30, v30, 4, v80
	ds_read_b128 v[56:59], v30 offset:36864
	v_xor_b32_e32 v30, v25, v82
	v_lshl_add_u32 v30, v30, 4, v80
	s_waitcnt lgkmcnt(0)
; __device__ __forceinline__ unsigned f2bf(float f) { return pk2(f, f) & 0xffffu; }
; #define LDS_WAIT() asm volatile("s_waitcnt lgkmcnt(0)" ::: "memory")
; __device__ __forceinline__ void norm_rope(u32x4 w0, u32x4 w1, const float* __restrict__ gain, int chunk, const float* rp, float scale, float* x) {
;     const unsigned ww[8] = {w0.x, w0.y, w0.z, w0.w, w1.x, w1.y, w1.z, w1.w};
;     float ss = 0.f;
; #pragma unroll
;     for (int i = 0; i < 8; ++i) { x[2 * i] = __uint_as_float(ww[i] << 16); x[2 * i + 1] = __uint_as_float(ww[i] & 0xffff0000u); ss += x[2 * i] * x[2 * i] + x[2 * i + 1] * x[2 * i + 1]; }
;     ss += dpp_perm<0xB1, 0xF>(ss); ss += dpp_perm<0x4E, 0xF>(ss);
;     const float inv = rsqrtf(ss * (1.0f / 64.0f) + 1e-6f);
; #pragma unroll
;     for (int i = 0; i < 16; ++i) x[i] = x[i] * inv * gain[chunk * 16 + i];
;     if (chunk == 0) rope16(x, rp);
; #pragma unroll
;     for (int i = 0; i < 16; ++i) x[i] *= scale;
; __device__ __forceinline__ void attn_unit(const AtArgs& A, unsigned char* lds, int unit, int tid, int wave, int lane) {
;     ...
;         LDS_WAIT();
; #pragma unroll
;         for (int r = 0; r < 4; ++r)
; #pragma unroll
;             for (int dt = 0; dt < 4; ++dt) PS[(fq * 4 + r) * PST + dt * 16 + fr] = (bf16)f2bf(o[dt][r]);
;         LDS_WAIT();
; #pragma unroll
;         for (int j = 0; j < 2; ++j) {
;             const int tk = (lane >> 3) + 8 * j, c16 = lane & 7;
;             const size_t t = (size_t)b * SEQ + nb * 128 + q0 + tk;
;             *(u32x4*)(YB + t * 512 + hq * 64 + c16 * 8) = *(const u32x4*)(PS + tk * PST + c16 * 8);
;         }
;         LDS_WAIT();
	v_mfma_f32_16x16x32_bf16 v[20:23], v[26:29], v[56:59], v[20:23]
	ds_read_b128 v[56:59], v30 offset:47872
	v_xor_b32_e32 v30, v25, v83
	v_lshl_add_u32 v30, v30, 4, v80
	s_waitcnt lgkmcnt(0)
	v_mfma_f32_16x16x32_bf16 v[16:19], v[26:29], v[56:59], v[16:19]
	ds_read_b128 v[56:59], v30 offset:58880
	v_xor_b32_e32 v25, v25, v84
	v_lshl_add_u32 v25, v25, 4, v81
	s_waitcnt lgkmcnt(0)
	v_mfma_f32_16x16x32_bf16 v[12:15], v[26:29], v[56:59], v[12:15]
	ds_read_b128 v[56:59], v25 offset:33024
	s_waitcnt lgkmcnt(0)
	v_cvt_pk_bf16_f32 v20, v20, s0
	s_waitcnt lgkmcnt(0)
	v_mfma_f32_16x16x32_bf16 v[8:11], v[26:29], v[56:59], v[8:11]
	v_cvt_pk_bf16_f32 v16, v16, s0
	s_nop 2
	v_cvt_pk_bf16_f32 v12, v12, s0
	ds_write_b16 v79, v20
	s_nop 1
	v_cvt_pk_bf16_f32 v8, v8, s0
	ds_write_b16 v79, v8 offset:96
	v_cvt_pk_bf16_f32 v8, v21, s0
	ds_write_b16 v79, v8 offset:336
	v_cvt_pk_bf16_f32 v8, v17, s0
	ds_write_b16 v79, v8 offset:368
	v_cvt_pk_bf16_f32 v8, v13, s0
	ds_write_b16 v79, v8 offset:400
	v_cvt_pk_bf16_f32 v8, v9, s0
	ds_write_b16 v79, v8 offset:432
	v_cvt_pk_bf16_f32 v8, v22, s0
	ds_write_b16 v79, v8 offset:672
	v_cvt_pk_bf16_f32 v8, v18, s0
	ds_write_b16 v79, v8 offset:704
	v_cvt_pk_bf16_f32 v8, v14, s0
	ds_write_b16 v79, v8 offset:736
	v_cvt_pk_bf16_f32 v8, v10, s0
	ds_write_b16 v79, v8 offset:768
	v_cvt_pk_bf16_f32 v8, v23, s0
	ds_write_b16 v79, v8 offset:1008
	v_cvt_pk_bf16_f32 v8, v19, s0
	ds_write_b16 v79, v8 offset:1040
	v_cvt_pk_bf16_f32 v8, v15, s0
	ds_write_b16 v79, v8 offset:1072
	v_cvt_pk_bf16_f32 v8, v11, s0
	ds_write_b16 v79, v16 offset:32
	ds_write_b16 v79, v12 offset:64
	ds_write_b16 v79, v8 offset:1104
	s_waitcnt lgkmcnt(0)
	ds_read_b128 v[8:11], v92
	v_lshl_add_u64 v[12:13], v[52:53], 0, s[20:21]
	s_mov_b32 s0, 0x1d800000
	v_add_co_u32_e32 v14, vcc, s0, v12
	s_mov_b32 s0, 0x1d802000
	s_nop 0
	v_addc_co_u32_e32 v15, vcc, 0, v13, vcc
	s_waitcnt lgkmcnt(0)
	global_store_dwordx4 v[14:15], v[8:11], off
	ds_read_b128 v[8:11], v92 offset:2688
	v_add_co_u32_e32 v12, vcc, s0, v12
	s_add_u32 s20, s20, 0x4000
	s_nop 0
	v_addc_co_u32_e32 v13, vcc, 0, v13, vcc
	s_waitcnt lgkmcnt(0)
	global_store_dwordx4 v[12:13], v[8:11], off
	s_waitcnt lgkmcnt(0)
	s_addc_u32 s21, s21, 0
	s_mov_b64 s[0:1], 0x400
	s_waitcnt vmcnt(2)
	v_mov_b64_e32 v[14:15], v[6:7]
	v_mov_b64_e32 v[10:11], v[2:3]
	v_add_u32_e32 v94, 2, v94
	v_lshl_add_u64 v[54:55], v[54:55], 0, s[0:1]
	s_cmp_lg_u32 s2, 64
	v_mov_b64_e32 v[12:13], v[4:5]
	v_mov_b64_e32 v[8:9], v[0:1]
	s_cbranch_scc0 .LBB0_492
.LBB0_511:
	s_nop 0
	s_nop 0
	s_nop 0
	s_nop 0
	s_nop 0
	s_nop 0
	s_nop 0
	s_nop 0
	s_nop 0
	s_nop 0
	s_nop 0
	v_and_b32_e32 v59, 0xffff0000, v15
	v_lshlrev_b32_e32 v58, 16, v15
	v_and_b32_e32 v15, 0xffff0000, v14
	v_lshlrev_b32_e32 v14, 16, v14
	v_mov_b32_e32 v96, v59
	v_mov_b32_e32 v97, v15
	v_mov_b32_e32 v60, v58
	v_mov_b32_e32 v61, v14
	v_pk_mul_f32 v[96:97], v[96:97], v[96:97]
	v_and_b32_e32 v57, 0xffff0000, v11
	v_pk_fma_f32 v[60:61], v[60:61], v[60:61], v[96:97]
	v_and_b32_e32 v97, 0xffff0000, v10
	v_lshlrev_b32_e32 v56, 16, v11
	v_lshlrev_b32_e32 v96, 16, v10
	v_mov_b32_e32 v98, v57
	v_mov_b32_e32 v99, v97
	v_mov_b32_e32 v10, v56
	v_mov_b32_e32 v11, v96
	v_pk_mul_f32 v[98:99], v[98:99], v[98:99]
	v_and_b32_e32 v101, 0xffff0000, v9
	v_pk_fma_f32 v[10:11], v[10:11], v[10:11], v[98:99]
	v_and_b32_e32 v99, 0xffff0000, v13
	v_lshlrev_b32_e32 v98, 16, v13
	v_and_b32_e32 v13, 0xffff0000, v12
	v_lshlrev_b32_e32 v12, 16, v12
	v_mov_b32_e32 v108, v13
	v_mov_b32_e32 v109, v99
	v_mov_b32_e32 v102, v12
	v_mov_b32_e32 v103, v98
	v_pk_mul_f32 v[108:109], v[108:109], v[108:109]
	v_lshlrev_b32_e32 v100, 16, v9
	v_pk_fma_f32 v[102:103], v[102:103], v[102:103], v[108:109]
	v_and_b32_e32 v9, 0xffff0000, v8
	v_lshlrev_b32_e32 v8, 16, v8
	v_mov_b32_e32 v110, v101
	v_mov_b32_e32 v111, v9
	v_add_f32_e32 v102, v102, v103
	v_mov_b32_e32 v108, v100
	v_mov_b32_e32 v109, v8
	v_pk_mul_f32 v[110:111], v[110:111], v[110:111]
	v_add_f32_e32 v61, v61, v102
	v_pk_fma_f32 v[108:109], v[108:109], v[108:109], v[110:111]
	v_add_f32_e32 v60, v60, v61
	v_add_f32_e32 v60, v109, v60
	v_add_f32_e32 v60, v108, v60
	v_add_f32_e32 v11, v11, v60
	v_add_f32_e32 v10, v10, v11
	s_nop 1
	v_add_f32_dpp v10, v10, v10 quad_perm:[1,0,3,2] row_mask:0xf bank_mask:0xf bound_ctrl:1
	s_nop 1
	v_add_f32_dpp v10, v10, v10 quad_perm:[2,3,0,1] row_mask:0xf bank_mask:0xf bound_ctrl:1
	v_fmamk_f32 v10, v10, 0x3c800000, v89
	v_cmp_gt_f32_e32 vcc, s34, v10
	v_mul_f32_e32 v11, 0x4b800000, v10
	s_nop 0
	v_cndmask_b32_e32 v10, v10, v11, vcc
	v_rsq_f32_e32 v10, v10
	s_nop 0
	v_mul_f32_e32 v11, 0x45800000, v10
	v_cndmask_b32_e32 v102, v10, v11, vcc
	v_pk_mul_f32 v[10:11], v[102:103], v[12:13] op_sel_hi:[0,1]
	v_pk_mul_f32 v[8:9], v[102:103], v[8:9] op_sel_hi:[0,1]
	s_nop 0
	v_pk_mul_f32 v[8:9], v[136:137], v[8:9]
	s_nop 0
	v_pk_mul_f32 v[60:61], v[128:129], v[10:11]
	v_pk_mul_f32 v[10:11], v[102:103], v[98:99] op_sel_hi:[0,1]
	v_pk_mul_f32 v[28:29], v[130:131], v[10:11]
	v_pk_mul_f32 v[10:11], v[102:103], v[14:15] op_sel_hi:[0,1]
	v_pk_mul_f32 v[24:25], v[132:133], v[10:11]
	v_pk_mul_f32 v[10:11], v[102:103], v[58:59] op_sel_hi:[0,1]
	v_pk_mul_f32 v[14:15], v[102:103], v[96:97] op_sel_hi:[0,1]
	v_pk_mul_f32 v[12:13], v[134:135], v[10:11]
	v_pk_mul_f32 v[10:11], v[102:103], v[100:101] op_sel_hi:[0,1]
	v_pk_mul_f32 v[14:15], v[140:141], v[14:15]
	v_pk_mul_f32 v[16:17], v[102:103], v[56:57] op_sel_hi:[0,1]
	v_pk_mul_f32 v[10:11], v[138:139], v[10:11]
	v_pk_mul_f32 v[16:17], v[16:17], v[142:143]
	s_and_saveexec_b64 s[0:1], s[40:41]
	s_cbranch_execz .LBB0_510
	global_load_dwordx4 v[18:21], v[54:55], off offset:16
	global_load_dwordx4 v[56:59], v[54:55], off offset:-16
	global_load_dwordx4 v[96:99], v[54:55], off
	global_load_dwordx4 v[100:103], v[54:55], off offset:-32
	s_waitcnt vmcnt(1)
	v_pk_mul_f32 v[26:27], v[60:61], v[96:97]
	v_pk_mul_f32 v[22:23], v[8:9], v[96:97]
	s_waitcnt vmcnt(0)
	v_pk_fma_f32 v[8:9], v[8:9], v[100:101], v[26:27]
	v_pk_mul_f32 v[26:27], v[10:11], v[98:99]
	v_pk_fma_f32 v[22:23], v[60:61], v[100:101], v[22:23] neg_lo:[0,0,1] neg_hi:[0,0,1]
	v_pk_fma_f32 v[26:27], v[28:29], v[102:103], v[26:27] neg_lo:[0,0,1] neg_hi:[0,0,1]
	v_pk_mul_f32 v[28:29], v[28:29], v[98:99]
	v_mov_b64_e32 v[60:61], v[22:23]
	v_pk_fma_f32 v[10:11], v[10:11], v[102:103], v[28:29]
	v_pk_mul_f32 v[28:29], v[14:15], v[18:19]
	v_pk_mul_f32 v[18:19], v[24:25], v[18:19]
	v_pk_fma_f32 v[28:29], v[24:25], v[56:57], v[28:29] neg_lo:[0,0,1] neg_hi:[0,0,1]
	v_pk_fma_f32 v[14:15], v[14:15], v[56:57], v[18:19]
	v_pk_mul_f32 v[18:19], v[16:17], v[20:21]
	v_mov_b64_e32 v[24:25], v[28:29]
	v_pk_fma_f32 v[18:19], v[12:13], v[58:59], v[18:19] neg_lo:[0,0,1] neg_hi:[0,0,1]
	v_pk_mul_f32 v[12:13], v[12:13], v[20:21]
	v_mov_b64_e32 v[28:29], v[26:27]
	v_pk_fma_f32 v[16:17], v[16:17], v[58:59], v[12:13]
	v_mov_b64_e32 v[12:13], v[18:19]
	s_branch .LBB0_510
